# K-loop counter/offset updates and exit compare hoisted into the last load segment (only the branch stays behind the loop-back barrier) for P2/P5/P7, on top of v100
# speedup vs baseline: 1.0031x; 1.0031x over previous
.Lprio_0:
.LBB0_124:
	ds_read_b128 v[138:141], v151
	ds_read_b128 v[142:145], v151 offset:1024
	ds_read_b128 v[158:161], v151 offset:2048
	ds_read_b128 v[162:165], v151 offset:3072
	ds_read_b128 v[166:169], v152
	ds_read_b128 v[170:173], v152 offset:1024
	ds_read_b128 v[174:177], v152 offset:2048
	ds_read_b128 v[178:181], v152 offset:3072
	s_add_i32 s47, s9, s10
	s_add_i32 s75, s47, 0x100
	s_add_i32 s13, s9, s11
	s_cmp_eq_u32 s9, s12
	s_cselect_b32 s13, s7, s13
	s_cselect_b32 s80, s6, s75
	s_add_i32 s75, s47, 0x80
	s_mov_b32 m0, s58
	ds_read_b128 v[182:185], v153
	ds_read_b128 v[186:189], v153 offset:1024
	buffer_load_dwordx4 v1, s[28:31], s75 offen lds
	s_mov_b32 m0, s59
	ds_read_b128 v[190:193], v153 offset:2048
	ds_read_b128 v[194:197], v153 offset:3072
	buffer_load_dwordx4 v147, s[28:31], s75 offen lds
	s_add_i32 s47, s47, 0x80080
	s_mov_b32 m0, s70
	ds_read_b128 v[198:201], v153 offset:4096
	ds_read_b128 v[202:205], v153 offset:5120
	buffer_load_dwordx4 v1, s[28:31], s47 offen lds
	s_mov_b32 m0, s71
	ds_read_b128 v[206:209], v153 offset:6144
	ds_read_b128 v[210:213], v153 offset:7168
	buffer_load_dwordx4 v147, s[28:31], s47 offen lds
	s_waitcnt vmcnt(8)
	s_waitcnt lgkmcnt(0)
	s_barrier
	s_waitcnt lgkmcnt(0)
	v_mfma_f32_16x16x32_bf16 v[130:133], v[138:141], v[182:185], v[130:133]
	v_mfma_f32_16x16x32_bf16 v[130:133], v[142:145], v[186:189], v[130:133]
	v_mfma_f32_16x16x32_bf16 v[114:117], v[142:145], v[194:197], v[114:117]
	v_mfma_f32_16x16x32_bf16 v[114:117], v[138:141], v[190:193], v[114:117]
	v_mfma_f32_16x16x32_bf16 v[98:101], v[138:141], v[198:201], v[98:101]
	v_mfma_f32_16x16x32_bf16 v[98:101], v[142:145], v[202:205], v[98:101]
	v_mfma_f32_16x16x32_bf16 v[82:85], v[142:145], v[210:213], v[82:85]
	v_mfma_f32_16x16x32_bf16 v[82:85], v[138:141], v[206:209], v[82:85]
	v_mfma_f32_16x16x32_bf16 v[78:81], v[162:165], v[210:213], v[78:81]
	v_mfma_f32_16x16x32_bf16 v[78:81], v[158:161], v[206:209], v[78:81]
	v_mfma_f32_16x16x32_bf16 v[94:97], v[158:161], v[198:201], v[94:97]
	v_mfma_f32_16x16x32_bf16 v[94:97], v[162:165], v[202:205], v[94:97]
	v_mfma_f32_16x16x32_bf16 v[110:113], v[162:165], v[194:197], v[110:113]
	v_mfma_f32_16x16x32_bf16 v[110:113], v[158:161], v[190:193], v[110:113]
	v_mfma_f32_16x16x32_bf16 v[126:129], v[158:161], v[182:185], v[126:129]
	v_mfma_f32_16x16x32_bf16 v[126:129], v[162:165], v[186:189], v[126:129]
	v_mfma_f32_16x16x32_bf16 v[122:125], v[166:169], v[182:185], v[122:125]
	v_mfma_f32_16x16x32_bf16 v[122:125], v[170:173], v[186:189], v[122:125]
	v_mfma_f32_16x16x32_bf16 v[106:109], v[170:173], v[194:197], v[106:109]
	v_mfma_f32_16x16x32_bf16 v[106:109], v[166:169], v[190:193], v[106:109]
	v_mfma_f32_16x16x32_bf16 v[90:93], v[166:169], v[198:201], v[90:93]
	v_mfma_f32_16x16x32_bf16 v[90:93], v[170:173], v[202:205], v[90:93]
	v_mfma_f32_16x16x32_bf16 v[74:77], v[170:173], v[210:213], v[74:77]
	v_mfma_f32_16x16x32_bf16 v[74:77], v[166:169], v[206:209], v[74:77]
	v_mfma_f32_16x16x32_bf16 v[70:73], v[178:181], v[210:213], v[70:73]
	v_mfma_f32_16x16x32_bf16 v[70:73], v[174:177], v[206:209], v[70:73]
	v_mfma_f32_16x16x32_bf16 v[86:89], v[174:177], v[198:201], v[86:89]
	v_mfma_f32_16x16x32_bf16 v[86:89], v[178:181], v[202:205], v[86:89]
	v_mfma_f32_16x16x32_bf16 v[102:105], v[178:181], v[194:197], v[102:105]
	v_mfma_f32_16x16x32_bf16 v[102:105], v[174:177], v[190:193], v[102:105]
	v_mfma_f32_16x16x32_bf16 v[118:121], v[174:177], v[182:185], v[118:121]
	v_mfma_f32_16x16x32_bf16 v[118:121], v[178:181], v[186:189], v[118:121]
	s_barrier
	s_mov_b32 m0, s91
	s_mov_b32 s75, s31
	ds_read_b128 v[182:185], v153 offset:16384
	ds_read_b128 v[186:189], v153 offset:17408
	buffer_load_dwordx4 v146, s[72:75], s13 offen lds
	s_mov_b32 m0, s93
	ds_read_b128 v[190:193], v153 offset:18432
	ds_read_b128 v[194:197], v153 offset:19456
	buffer_load_dwordx4 v148, s[72:75], s13 offen lds
	s_add_i32 s47, s13, 0x80000
	s_mov_b32 m0, s95
	ds_read_b128 v[198:201], v153 offset:20480
	ds_read_b128 v[202:205], v153 offset:21504
	buffer_load_dwordx4 v146, s[72:75], s47 offen lds
	s_mov_b32 m0, s35
	ds_read_b128 v[206:209], v153 offset:22528
	ds_read_b128 v[210:213], v153 offset:23552
	buffer_load_dwordx4 v148, s[72:75], s47 offen lds
	s_waitcnt vmcnt(6)
	s_waitcnt lgkmcnt(0)
	s_barrier
	s_waitcnt lgkmcnt(0)
	v_mfma_f32_16x16x32_bf16 v[66:69], v[138:141], v[182:185], v[66:69]
	v_mfma_f32_16x16x32_bf16 v[66:69], v[142:145], v[186:189], v[66:69]
	v_mfma_f32_16x16x32_bf16 v[50:53], v[142:145], v[194:197], v[50:53]
	v_mfma_f32_16x16x32_bf16 v[50:53], v[138:141], v[190:193], v[50:53]
	v_mfma_f32_16x16x32_bf16 v[34:37], v[138:141], v[198:201], v[34:37]
	v_mfma_f32_16x16x32_bf16 v[34:37], v[142:145], v[202:205], v[34:37]
	v_mfma_f32_16x16x32_bf16 v[18:21], v[142:145], v[210:213], v[18:21]
	v_mfma_f32_16x16x32_bf16 v[18:21], v[138:141], v[206:209], v[18:21]
	v_mfma_f32_16x16x32_bf16 v[14:17], v[162:165], v[210:213], v[14:17]
	v_mfma_f32_16x16x32_bf16 v[14:17], v[158:161], v[206:209], v[14:17]
	v_mfma_f32_16x16x32_bf16 v[30:33], v[158:161], v[198:201], v[30:33]
	v_mfma_f32_16x16x32_bf16 v[30:33], v[162:165], v[202:205], v[30:33]
	v_mfma_f32_16x16x32_bf16 v[46:49], v[162:165], v[194:197], v[46:49]
	v_mfma_f32_16x16x32_bf16 v[46:49], v[158:161], v[190:193], v[46:49]
	v_mfma_f32_16x16x32_bf16 v[62:65], v[158:161], v[182:185], v[62:65]
	v_mfma_f32_16x16x32_bf16 v[62:65], v[162:165], v[186:189], v[62:65]
	v_mfma_f32_16x16x32_bf16 v[58:61], v[166:169], v[182:185], v[58:61]
	v_mfma_f32_16x16x32_bf16 v[58:61], v[170:173], v[186:189], v[58:61]
	v_mfma_f32_16x16x32_bf16 v[42:45], v[170:173], v[194:197], v[42:45]
	v_mfma_f32_16x16x32_bf16 v[42:45], v[166:169], v[190:193], v[42:45]
	v_mfma_f32_16x16x32_bf16 v[26:29], v[166:169], v[198:201], v[26:29]
	v_mfma_f32_16x16x32_bf16 v[26:29], v[170:173], v[202:205], v[26:29]
	v_mfma_f32_16x16x32_bf16 v[10:13], v[170:173], v[210:213], v[10:13]
	v_mfma_f32_16x16x32_bf16 v[10:13], v[166:169], v[206:209], v[10:13]
	v_mfma_f32_16x16x32_bf16 v[4:7], v[174:177], v[206:209], v[6:9]
	v_mfma_f32_16x16x32_bf16 v[4:7], v[178:181], v[210:213], v[4:7]
	v_mfma_f32_16x16x32_bf16 v[22:25], v[174:177], v[198:201], v[22:25]
	v_mfma_f32_16x16x32_bf16 v[22:25], v[178:181], v[202:205], v[22:25]
	v_mfma_f32_16x16x32_bf16 v[38:41], v[178:181], v[194:197], v[38:41]
	v_mfma_f32_16x16x32_bf16 v[38:41], v[174:177], v[190:193], v[38:41]
	v_mfma_f32_16x16x32_bf16 v[54:57], v[174:177], v[182:185], v[54:57]
	v_mfma_f32_16x16x32_bf16 v[54:57], v[178:181], v[186:189], v[54:57]
	s_barrier
	ds_read_b128 v[138:141], v154
	ds_read_b128 v[142:145], v154 offset:1024
	ds_read_b128 v[158:161], v154 offset:2048
	ds_read_b128 v[162:165], v154 offset:3072
	ds_read_b128 v[166:169], v155
	ds_read_b128 v[170:173], v155 offset:1024
	ds_read_b128 v[174:177], v155 offset:2048
	ds_read_b128 v[178:181], v155 offset:3072
	s_mov_b32 m0, s77
	ds_read_b128 v[182:185], v153 offset:32768
	ds_read_b128 v[186:189], v153 offset:33792
	buffer_load_dwordx4 v1, s[28:31], s80 offen lds
	s_mov_b32 m0, s84
	ds_read_b128 v[190:193], v153 offset:34816
	ds_read_b128 v[194:197], v153 offset:35840
	buffer_load_dwordx4 v147, s[28:31], s80 offen lds
	s_add_i32 s80, s80, 0x80000
	s_mov_b32 m0, s85
	ds_read_b128 v[198:201], v153 offset:36864
	ds_read_b128 v[202:205], v153 offset:37888
	buffer_load_dwordx4 v1, s[28:31], s80 offen lds
	s_mov_b32 m0, s48
	ds_read_b128 v[206:209], v153 offset:38912
	ds_read_b128 v[210:213], v153 offset:39936
	buffer_load_dwordx4 v147, s[28:31], s80 offen lds
	s_waitcnt vmcnt(8)
	s_waitcnt lgkmcnt(0)
	s_barrier
	s_waitcnt lgkmcnt(0)
	v_mfma_f32_16x16x32_bf16 v[130:133], v[138:141], v[182:185], v[130:133]
	v_mfma_f32_16x16x32_bf16 v[130:133], v[142:145], v[186:189], v[130:133]
	v_mfma_f32_16x16x32_bf16 v[114:117], v[142:145], v[194:197], v[114:117]
	v_mfma_f32_16x16x32_bf16 v[114:117], v[138:141], v[190:193], v[114:117]
	v_mfma_f32_16x16x32_bf16 v[98:101], v[138:141], v[198:201], v[98:101]
	v_mfma_f32_16x16x32_bf16 v[98:101], v[142:145], v[202:205], v[98:101]
	v_mfma_f32_16x16x32_bf16 v[82:85], v[142:145], v[210:213], v[82:85]
	v_mfma_f32_16x16x32_bf16 v[82:85], v[138:141], v[206:209], v[82:85]
	v_mfma_f32_16x16x32_bf16 v[78:81], v[162:165], v[210:213], v[78:81]
	v_mfma_f32_16x16x32_bf16 v[78:81], v[158:161], v[206:209], v[78:81]
	v_mfma_f32_16x16x32_bf16 v[94:97], v[158:161], v[198:201], v[94:97]
	v_mfma_f32_16x16x32_bf16 v[94:97], v[162:165], v[202:205], v[94:97]
	v_mfma_f32_16x16x32_bf16 v[110:113], v[162:165], v[194:197], v[110:113]
	v_mfma_f32_16x16x32_bf16 v[110:113], v[158:161], v[190:193], v[110:113]
	v_mfma_f32_16x16x32_bf16 v[126:129], v[158:161], v[182:185], v[126:129]
	v_mfma_f32_16x16x32_bf16 v[126:129], v[162:165], v[186:189], v[126:129]
	v_mfma_f32_16x16x32_bf16 v[122:125], v[166:169], v[182:185], v[122:125]
	v_mfma_f32_16x16x32_bf16 v[122:125], v[170:173], v[186:189], v[122:125]
	v_mfma_f32_16x16x32_bf16 v[106:109], v[170:173], v[194:197], v[106:109]
	v_mfma_f32_16x16x32_bf16 v[106:109], v[166:169], v[190:193], v[106:109]
	v_mfma_f32_16x16x32_bf16 v[90:93], v[166:169], v[198:201], v[90:93]
	v_mfma_f32_16x16x32_bf16 v[90:93], v[170:173], v[202:205], v[90:93]
	v_mfma_f32_16x16x32_bf16 v[74:77], v[170:173], v[210:213], v[74:77]
	v_mfma_f32_16x16x32_bf16 v[74:77], v[166:169], v[206:209], v[74:77]
	v_mfma_f32_16x16x32_bf16 v[70:73], v[178:181], v[210:213], v[70:73]
	v_mfma_f32_16x16x32_bf16 v[70:73], v[174:177], v[206:209], v[70:73]
	v_mfma_f32_16x16x32_bf16 v[86:89], v[174:177], v[198:201], v[86:89]
	v_mfma_f32_16x16x32_bf16 v[86:89], v[178:181], v[202:205], v[86:89]
	v_mfma_f32_16x16x32_bf16 v[102:105], v[178:181], v[194:197], v[102:105]
	v_mfma_f32_16x16x32_bf16 v[102:105], v[174:177], v[190:193], v[102:105]
	v_mfma_f32_16x16x32_bf16 v[118:121], v[174:177], v[182:185], v[118:121]
	v_mfma_f32_16x16x32_bf16 v[118:121], v[178:181], v[186:189], v[118:121]
	s_barrier
	s_mov_b32 m0, s78
	s_add_i32 s47, s13, 0x80
	ds_read_b128 v[182:185], v153 offset:49152
	ds_read_b128 v[186:189], v153 offset:50176
	buffer_load_dwordx4 v146, s[72:75], s47 offen lds
	s_mov_b32 m0, s79
	ds_read_b128 v[190:193], v153 offset:51200
	ds_read_b128 v[194:197], v153 offset:52224
	buffer_load_dwordx4 v148, s[72:75], s47 offen lds
	s_add_i32 s13, s13, 0x80080
	s_mov_b32 m0, s86
	ds_read_b128 v[198:201], v153 offset:53248
	ds_read_b128 v[202:205], v153 offset:54272
	buffer_load_dwordx4 v146, s[72:75], s13 offen lds
	s_mov_b32 m0, s87
	ds_read_b128 v[206:209], v153 offset:55296
	ds_read_b128 v[210:213], v153 offset:56320
	buffer_load_dwordx4 v148, s[72:75], s13 offen lds
	s_add_i32 s8, s8, 2
	s_addk_i32 s10, 0x100
	s_addk_i32 s11, 0x100
	s_addk_i32 s12, 0xff00
	s_cmp_gt_u32 s8, 29
	s_waitcnt vmcnt(6)
	s_waitcnt lgkmcnt(0)
	s_barrier
	s_waitcnt lgkmcnt(0)
	v_mfma_f32_16x16x32_bf16 v[66:69], v[138:141], v[182:185], v[66:69]
	v_mfma_f32_16x16x32_bf16 v[66:69], v[142:145], v[186:189], v[66:69]
	v_mfma_f32_16x16x32_bf16 v[50:53], v[142:145], v[194:197], v[50:53]
	v_mfma_f32_16x16x32_bf16 v[50:53], v[138:141], v[190:193], v[50:53]
	v_mfma_f32_16x16x32_bf16 v[34:37], v[138:141], v[198:201], v[34:37]
	v_mfma_f32_16x16x32_bf16 v[34:37], v[142:145], v[202:205], v[34:37]
	v_mfma_f32_16x16x32_bf16 v[18:21], v[142:145], v[210:213], v[18:21]
	v_mfma_f32_16x16x32_bf16 v[18:21], v[138:141], v[206:209], v[18:21]
	v_mfma_f32_16x16x32_bf16 v[14:17], v[162:165], v[210:213], v[14:17]
	v_mfma_f32_16x16x32_bf16 v[14:17], v[158:161], v[206:209], v[14:17]
	v_mfma_f32_16x16x32_bf16 v[30:33], v[158:161], v[198:201], v[30:33]
	v_mfma_f32_16x16x32_bf16 v[30:33], v[162:165], v[202:205], v[30:33]
	v_mfma_f32_16x16x32_bf16 v[46:49], v[162:165], v[194:197], v[46:49]
	v_mfma_f32_16x16x32_bf16 v[46:49], v[158:161], v[190:193], v[46:49]
	v_mfma_f32_16x16x32_bf16 v[62:65], v[158:161], v[182:185], v[62:65]
	v_mfma_f32_16x16x32_bf16 v[62:65], v[162:165], v[186:189], v[62:65]
	v_mfma_f32_16x16x32_bf16 v[58:61], v[166:169], v[182:185], v[58:61]
	v_mfma_f32_16x16x32_bf16 v[58:61], v[170:173], v[186:189], v[58:61]
	v_mfma_f32_16x16x32_bf16 v[42:45], v[170:173], v[194:197], v[42:45]
	v_mfma_f32_16x16x32_bf16 v[42:45], v[166:169], v[190:193], v[42:45]
	v_mfma_f32_16x16x32_bf16 v[26:29], v[166:169], v[198:201], v[26:29]
	v_mfma_f32_16x16x32_bf16 v[26:29], v[170:173], v[202:205], v[26:29]
	v_mfma_f32_16x16x32_bf16 v[8:11], v[166:169], v[206:209], v[10:13]
	v_mfma_f32_16x16x32_bf16 v[10:13], v[170:173], v[210:213], v[8:11]
	v_mfma_f32_16x16x32_bf16 v[4:7], v[174:177], v[206:209], v[4:7]
	v_mfma_f32_16x16x32_bf16 v[6:9], v[178:181], v[210:213], v[4:7]
	v_mfma_f32_16x16x32_bf16 v[22:25], v[174:177], v[198:201], v[22:25]
	v_mfma_f32_16x16x32_bf16 v[22:25], v[178:181], v[202:205], v[22:25]
	v_mfma_f32_16x16x32_bf16 v[38:41], v[178:181], v[194:197], v[38:41]
	v_mfma_f32_16x16x32_bf16 v[38:41], v[174:177], v[190:193], v[38:41]
	v_mfma_f32_16x16x32_bf16 v[54:57], v[174:177], v[182:185], v[54:57]
	v_mfma_f32_16x16x32_bf16 v[54:57], v[178:181], v[186:189], v[54:57]
	s_barrier
	s_cbranch_scc0 .LBB0_124
	s_setprio 0
	v_readlane_b32 s6, v254, 26
	v_readlane_b32 s7, v254, 27
	s_and_b64 vcc, exec, s[6:7]
	s_cbranch_vccz .LBB0_127
	s_barrier

.Lprio_2:
.LBB0_605:
	v_add_u32_e32 v141, 0x10000, v139
	ds_read_b128 v[142:145], v141
	ds_read_b128 v[146:149], v141 offset:1024
	ds_read_b128 v[154:157], v141 offset:2048
	ds_read_b128 v[158:161], v141 offset:3072
	v_add_u32_e32 v141, 0x14000, v139
	ds_read_b128 v[162:165], v141
	ds_read_b128 v[166:169], v141 offset:1024
	ds_read_b128 v[170:173], v141 offset:2048
	ds_read_b128 v[174:177], v141 offset:3072
	s_add_i32 s47, s64, s82
	s_add_i32 s84, s47, 0x100
	s_add_i32 s83, s11, s82
	s_cmpk_eq_i32 s82, 0xf00
	s_cselect_b32 s83, s80, s83
	s_cselect_b32 s84, s79, s84
	s_add_i32 s85, s47, 0x80
	s_mov_b32 m0, s71
	ds_read_b128 v[178:181], v140
	ds_read_b128 v[182:185], v140 offset:1024
	buffer_load_dwordx4 v135, s[12:15], s85 offen lds
	s_mov_b32 m0, s72
	ds_read_b128 v[186:189], v140 offset:2048
	ds_read_b128 v[190:193], v140 offset:3072
	buffer_load_dwordx4 v137, s[12:15], s85 offen lds
	s_add_i32 s47, s47, 0x80080
	s_mov_b32 m0, s73
	ds_read_b128 v[194:197], v140 offset:4096
	ds_read_b128 v[198:201], v140 offset:5120
	buffer_load_dwordx4 v135, s[12:15], s47 offen lds
	s_mov_b32 m0, s74
	ds_read_b128 v[202:205], v140 offset:6144
	ds_read_b128 v[206:209], v140 offset:7168
	buffer_load_dwordx4 v137, s[12:15], s47 offen lds
	s_waitcnt vmcnt(8)
	s_waitcnt lgkmcnt(0)
	s_barrier
	s_waitcnt lgkmcnt(0)
	v_mfma_f32_16x16x32_bf16 v[126:129], v[142:145], v[178:181], v[126:129]
	v_mfma_f32_16x16x32_bf16 v[126:129], v[146:149], v[182:185], v[126:129]
	v_mfma_f32_16x16x32_bf16 v[110:113], v[146:149], v[190:193], v[110:113]
	v_mfma_f32_16x16x32_bf16 v[110:113], v[142:145], v[186:189], v[110:113]
	v_mfma_f32_16x16x32_bf16 v[94:97], v[142:145], v[194:197], v[94:97]
	v_mfma_f32_16x16x32_bf16 v[94:97], v[146:149], v[198:201], v[94:97]
	v_mfma_f32_16x16x32_bf16 v[78:81], v[146:149], v[206:209], v[78:81]
	v_mfma_f32_16x16x32_bf16 v[78:81], v[142:145], v[202:205], v[78:81]
	v_mfma_f32_16x16x32_bf16 v[74:77], v[158:161], v[206:209], v[74:77]
	v_mfma_f32_16x16x32_bf16 v[74:77], v[154:157], v[202:205], v[74:77]
	v_mfma_f32_16x16x32_bf16 v[90:93], v[154:157], v[194:197], v[90:93]
	v_mfma_f32_16x16x32_bf16 v[90:93], v[158:161], v[198:201], v[90:93]
	v_mfma_f32_16x16x32_bf16 v[106:109], v[158:161], v[190:193], v[106:109]
	v_mfma_f32_16x16x32_bf16 v[106:109], v[154:157], v[186:189], v[106:109]
	v_mfma_f32_16x16x32_bf16 v[122:125], v[154:157], v[178:181], v[122:125]
	v_mfma_f32_16x16x32_bf16 v[122:125], v[158:161], v[182:185], v[122:125]
	v_mfma_f32_16x16x32_bf16 v[118:121], v[162:165], v[178:181], v[118:121]
	v_mfma_f32_16x16x32_bf16 v[118:121], v[166:169], v[182:185], v[118:121]
	v_mfma_f32_16x16x32_bf16 v[102:105], v[166:169], v[190:193], v[102:105]
	v_mfma_f32_16x16x32_bf16 v[102:105], v[162:165], v[186:189], v[102:105]
	v_mfma_f32_16x16x32_bf16 v[86:89], v[162:165], v[194:197], v[86:89]
	v_mfma_f32_16x16x32_bf16 v[86:89], v[166:169], v[198:201], v[86:89]
	v_mfma_f32_16x16x32_bf16 v[70:73], v[166:169], v[206:209], v[70:73]
	v_mfma_f32_16x16x32_bf16 v[70:73], v[162:165], v[202:205], v[70:73]
	v_mfma_f32_16x16x32_bf16 v[66:69], v[174:177], v[206:209], v[66:69]
	v_mfma_f32_16x16x32_bf16 v[66:69], v[170:173], v[202:205], v[66:69]
	v_mfma_f32_16x16x32_bf16 v[82:85], v[170:173], v[194:197], v[82:85]
	v_mfma_f32_16x16x32_bf16 v[82:85], v[174:177], v[198:201], v[82:85]
	v_mfma_f32_16x16x32_bf16 v[98:101], v[174:177], v[190:193], v[98:101]
	v_mfma_f32_16x16x32_bf16 v[98:101], v[170:173], v[186:189], v[98:101]
	v_mfma_f32_16x16x32_bf16 v[114:117], v[170:173], v[178:181], v[114:117]
	v_mfma_f32_16x16x32_bf16 v[114:117], v[174:177], v[182:185], v[114:117]
	s_barrier
	s_mov_b32 m0, s58
	s_mov_b32 s47, s15
	ds_read_b128 v[178:181], v140 offset:16384
	ds_read_b128 v[182:185], v140 offset:17408
	buffer_load_dwordx4 v136, s[44:47], s83 offen lds
	s_mov_b32 m0, s60
	ds_read_b128 v[186:189], v140 offset:18432
	ds_read_b128 v[190:193], v140 offset:19456
	buffer_load_dwordx4 v138, s[44:47], s83 offen lds
	s_add_i32 s85, s83, 0x80000
	s_mov_b32 m0, s61
	ds_read_b128 v[194:197], v140 offset:20480
	ds_read_b128 v[198:201], v140 offset:21504
	buffer_load_dwordx4 v136, s[44:47], s85 offen lds
	s_mov_b32 m0, s62
	ds_read_b128 v[202:205], v140 offset:22528
	ds_read_b128 v[206:209], v140 offset:23552
	buffer_load_dwordx4 v138, s[44:47], s85 offen lds
	s_waitcnt vmcnt(6)
	s_waitcnt lgkmcnt(0)
	s_barrier
	s_waitcnt lgkmcnt(0)
	v_mfma_f32_16x16x32_bf16 v[62:65], v[142:145], v[178:181], v[62:65]
	v_mfma_f32_16x16x32_bf16 v[62:65], v[146:149], v[182:185], v[62:65]
	v_mfma_f32_16x16x32_bf16 v[46:49], v[146:149], v[190:193], v[46:49]
	v_mfma_f32_16x16x32_bf16 v[46:49], v[142:145], v[186:189], v[46:49]
	v_mfma_f32_16x16x32_bf16 v[30:33], v[142:145], v[194:197], v[30:33]
	v_mfma_f32_16x16x32_bf16 v[30:33], v[146:149], v[198:201], v[30:33]
	v_mfma_f32_16x16x32_bf16 v[14:17], v[146:149], v[206:209], v[14:17]
	v_mfma_f32_16x16x32_bf16 v[14:17], v[142:145], v[202:205], v[14:17]
	v_mfma_f32_16x16x32_bf16 v[10:13], v[158:161], v[206:209], v[10:13]
	v_mfma_f32_16x16x32_bf16 v[10:13], v[154:157], v[202:205], v[10:13]
	v_mfma_f32_16x16x32_bf16 v[26:29], v[154:157], v[194:197], v[26:29]
	v_mfma_f32_16x16x32_bf16 v[26:29], v[158:161], v[198:201], v[26:29]
	v_mfma_f32_16x16x32_bf16 v[42:45], v[158:161], v[190:193], v[42:45]
	v_mfma_f32_16x16x32_bf16 v[42:45], v[154:157], v[186:189], v[42:45]
	v_mfma_f32_16x16x32_bf16 v[58:61], v[154:157], v[178:181], v[58:61]
	v_mfma_f32_16x16x32_bf16 v[58:61], v[158:161], v[182:185], v[58:61]
	v_mfma_f32_16x16x32_bf16 v[54:57], v[162:165], v[178:181], v[54:57]
	v_mfma_f32_16x16x32_bf16 v[54:57], v[166:169], v[182:185], v[54:57]
	v_mfma_f32_16x16x32_bf16 v[38:41], v[166:169], v[190:193], v[38:41]
	v_mfma_f32_16x16x32_bf16 v[38:41], v[162:165], v[186:189], v[38:41]
	v_mfma_f32_16x16x32_bf16 v[22:25], v[162:165], v[194:197], v[22:25]
	v_mfma_f32_16x16x32_bf16 v[22:25], v[166:169], v[198:201], v[22:25]
	v_mfma_f32_16x16x32_bf16 v[6:9], v[166:169], v[206:209], v[6:9]
	v_mfma_f32_16x16x32_bf16 v[6:9], v[162:165], v[202:205], v[6:9]
	v_mfma_f32_16x16x32_bf16 v[2:5], v[174:177], v[206:209], v[2:5]
	v_mfma_f32_16x16x32_bf16 v[2:5], v[170:173], v[202:205], v[2:5]
	v_mfma_f32_16x16x32_bf16 v[18:21], v[170:173], v[194:197], v[18:21]
	v_mfma_f32_16x16x32_bf16 v[18:21], v[174:177], v[198:201], v[18:21]
	v_mfma_f32_16x16x32_bf16 v[34:37], v[174:177], v[190:193], v[34:37]
	v_mfma_f32_16x16x32_bf16 v[34:37], v[170:173], v[186:189], v[34:37]
	v_mfma_f32_16x16x32_bf16 v[50:53], v[170:173], v[178:181], v[50:53]
	v_mfma_f32_16x16x32_bf16 v[50:53], v[174:177], v[182:185], v[50:53]
	s_barrier
	v_add_u32_e32 v141, 0x18000, v139
	ds_read_b128 v[142:145], v141
	ds_read_b128 v[146:149], v141 offset:1024
	ds_read_b128 v[154:157], v141 offset:2048
	ds_read_b128 v[158:161], v141 offset:3072
	v_add_u32_e32 v141, 0x1c000, v139
	ds_read_b128 v[162:165], v141
	ds_read_b128 v[166:169], v141 offset:1024
	ds_read_b128 v[170:173], v141 offset:2048
	ds_read_b128 v[174:177], v141 offset:3072
	s_mov_b32 m0, s51
	ds_read_b128 v[178:181], v140 offset:32768
	ds_read_b128 v[182:185], v140 offset:33792
	buffer_load_dwordx4 v135, s[12:15], s84 offen lds
	s_mov_b32 m0, s63
	ds_read_b128 v[186:189], v140 offset:34816
	ds_read_b128 v[190:193], v140 offset:35840
	buffer_load_dwordx4 v137, s[12:15], s84 offen lds
	s_add_i32 s84, s84, 0x80000
	s_mov_b32 m0, s65
	ds_read_b128 v[194:197], v140 offset:36864
	ds_read_b128 v[198:201], v140 offset:37888
	buffer_load_dwordx4 v135, s[12:15], s84 offen lds
	s_mov_b32 m0, s66
	ds_read_b128 v[202:205], v140 offset:38912
	ds_read_b128 v[206:209], v140 offset:39936
	buffer_load_dwordx4 v137, s[12:15], s84 offen lds
	s_waitcnt vmcnt(8)
	s_waitcnt lgkmcnt(0)
	s_barrier
	s_waitcnt lgkmcnt(0)
	v_mfma_f32_16x16x32_bf16 v[126:129], v[142:145], v[178:181], v[126:129]
	v_mfma_f32_16x16x32_bf16 v[126:129], v[146:149], v[182:185], v[126:129]
	v_mfma_f32_16x16x32_bf16 v[110:113], v[146:149], v[190:193], v[110:113]
	v_mfma_f32_16x16x32_bf16 v[110:113], v[142:145], v[186:189], v[110:113]
	v_mfma_f32_16x16x32_bf16 v[94:97], v[142:145], v[194:197], v[94:97]
	v_mfma_f32_16x16x32_bf16 v[94:97], v[146:149], v[198:201], v[94:97]
	v_mfma_f32_16x16x32_bf16 v[78:81], v[146:149], v[206:209], v[78:81]
	v_mfma_f32_16x16x32_bf16 v[78:81], v[142:145], v[202:205], v[78:81]
	v_mfma_f32_16x16x32_bf16 v[74:77], v[158:161], v[206:209], v[74:77]
	v_mfma_f32_16x16x32_bf16 v[74:77], v[154:157], v[202:205], v[74:77]
	v_mfma_f32_16x16x32_bf16 v[90:93], v[154:157], v[194:197], v[90:93]
	v_mfma_f32_16x16x32_bf16 v[90:93], v[158:161], v[198:201], v[90:93]
	v_mfma_f32_16x16x32_bf16 v[106:109], v[158:161], v[190:193], v[106:109]
	v_mfma_f32_16x16x32_bf16 v[106:109], v[154:157], v[186:189], v[106:109]
	v_mfma_f32_16x16x32_bf16 v[122:125], v[154:157], v[178:181], v[122:125]
	v_mfma_f32_16x16x32_bf16 v[122:125], v[158:161], v[182:185], v[122:125]
	v_mfma_f32_16x16x32_bf16 v[118:121], v[162:165], v[178:181], v[118:121]
	v_mfma_f32_16x16x32_bf16 v[118:121], v[166:169], v[182:185], v[118:121]
	v_mfma_f32_16x16x32_bf16 v[102:105], v[166:169], v[190:193], v[102:105]
	v_mfma_f32_16x16x32_bf16 v[102:105], v[162:165], v[186:189], v[102:105]
	v_mfma_f32_16x16x32_bf16 v[86:89], v[162:165], v[194:197], v[86:89]
	v_mfma_f32_16x16x32_bf16 v[86:89], v[166:169], v[198:201], v[86:89]
	v_mfma_f32_16x16x32_bf16 v[70:73], v[166:169], v[206:209], v[70:73]
	v_mfma_f32_16x16x32_bf16 v[70:73], v[162:165], v[202:205], v[70:73]
	v_mfma_f32_16x16x32_bf16 v[66:69], v[174:177], v[206:209], v[66:69]
	v_mfma_f32_16x16x32_bf16 v[66:69], v[170:173], v[202:205], v[66:69]
	v_mfma_f32_16x16x32_bf16 v[82:85], v[170:173], v[194:197], v[82:85]
	v_mfma_f32_16x16x32_bf16 v[82:85], v[174:177], v[198:201], v[82:85]
	v_mfma_f32_16x16x32_bf16 v[98:101], v[174:177], v[190:193], v[98:101]
	v_mfma_f32_16x16x32_bf16 v[98:101], v[170:173], v[186:189], v[98:101]
	v_mfma_f32_16x16x32_bf16 v[114:117], v[170:173], v[178:181], v[114:117]
	v_mfma_f32_16x16x32_bf16 v[114:117], v[174:177], v[182:185], v[114:117]
	s_barrier
	s_mov_b32 m0, s67
	s_or_b32 s84, s83, 0x80
	ds_read_b128 v[178:181], v140 offset:49152
	ds_read_b128 v[182:185], v140 offset:50176
	buffer_load_dwordx4 v136, s[44:47], s84 offen lds
	s_mov_b32 m0, s68
	ds_read_b128 v[186:189], v140 offset:51200
	ds_read_b128 v[190:193], v140 offset:52224
	buffer_load_dwordx4 v138, s[44:47], s84 offen lds
	s_add_i32 s83, s83, 0x80080
	s_mov_b32 m0, s69
	ds_read_b128 v[194:197], v140 offset:53248
	ds_read_b128 v[198:201], v140 offset:54272
	buffer_load_dwordx4 v136, s[44:47], s83 offen lds
	s_mov_b32 m0, s70
	ds_read_b128 v[202:205], v140 offset:55296
	ds_read_b128 v[206:209], v140 offset:56320
	buffer_load_dwordx4 v138, s[44:47], s83 offen lds
	s_add_i32 s81, s81, 2
	s_addk_i32 s82, 0x100
	s_cmp_gt_u32 s81, 29
	s_waitcnt vmcnt(6)
	s_waitcnt lgkmcnt(0)
	s_barrier
	s_waitcnt lgkmcnt(0)
	v_mfma_f32_16x16x32_bf16 v[62:65], v[142:145], v[178:181], v[62:65]
	v_mfma_f32_16x16x32_bf16 v[62:65], v[146:149], v[182:185], v[62:65]
	v_mfma_f32_16x16x32_bf16 v[46:49], v[146:149], v[190:193], v[46:49]
	v_mfma_f32_16x16x32_bf16 v[46:49], v[142:145], v[186:189], v[46:49]
	v_mfma_f32_16x16x32_bf16 v[30:33], v[142:145], v[194:197], v[30:33]
	v_mfma_f32_16x16x32_bf16 v[30:33], v[146:149], v[198:201], v[30:33]
	v_mfma_f32_16x16x32_bf16 v[14:17], v[146:149], v[206:209], v[14:17]
	v_mfma_f32_16x16x32_bf16 v[14:17], v[142:145], v[202:205], v[14:17]
	v_mfma_f32_16x16x32_bf16 v[10:13], v[158:161], v[206:209], v[10:13]
	v_mfma_f32_16x16x32_bf16 v[10:13], v[154:157], v[202:205], v[10:13]
	v_mfma_f32_16x16x32_bf16 v[26:29], v[154:157], v[194:197], v[26:29]
	v_mfma_f32_16x16x32_bf16 v[26:29], v[158:161], v[198:201], v[26:29]
	v_mfma_f32_16x16x32_bf16 v[42:45], v[158:161], v[190:193], v[42:45]
	v_mfma_f32_16x16x32_bf16 v[42:45], v[154:157], v[186:189], v[42:45]
	v_mfma_f32_16x16x32_bf16 v[58:61], v[154:157], v[178:181], v[58:61]
	v_mfma_f32_16x16x32_bf16 v[58:61], v[158:161], v[182:185], v[58:61]
	v_mfma_f32_16x16x32_bf16 v[54:57], v[162:165], v[178:181], v[54:57]
	v_mfma_f32_16x16x32_bf16 v[54:57], v[166:169], v[182:185], v[54:57]
	v_mfma_f32_16x16x32_bf16 v[38:41], v[166:169], v[190:193], v[38:41]
	v_mfma_f32_16x16x32_bf16 v[38:41], v[162:165], v[186:189], v[38:41]
	v_mfma_f32_16x16x32_bf16 v[22:25], v[162:165], v[194:197], v[22:25]
	v_mfma_f32_16x16x32_bf16 v[22:25], v[166:169], v[198:201], v[22:25]
	v_mfma_f32_16x16x32_bf16 v[6:9], v[166:169], v[206:209], v[6:9]
	v_mfma_f32_16x16x32_bf16 v[6:9], v[162:165], v[202:205], v[6:9]
	v_mfma_f32_16x16x32_bf16 v[2:5], v[174:177], v[206:209], v[2:5]
	v_mfma_f32_16x16x32_bf16 v[2:5], v[170:173], v[202:205], v[2:5]
	v_mfma_f32_16x16x32_bf16 v[18:21], v[170:173], v[194:197], v[18:21]
	v_mfma_f32_16x16x32_bf16 v[18:21], v[174:177], v[198:201], v[18:21]
	v_mfma_f32_16x16x32_bf16 v[34:37], v[174:177], v[190:193], v[34:37]
	v_mfma_f32_16x16x32_bf16 v[34:37], v[170:173], v[186:189], v[34:37]
	v_mfma_f32_16x16x32_bf16 v[50:53], v[170:173], v[178:181], v[50:53]
	v_mfma_f32_16x16x32_bf16 v[50:53], v[174:177], v[182:185], v[50:53]
	s_barrier
	s_cbranch_scc0 .LBB0_605
	s_setprio 0
	s_andn2_b64 vcc, exec, s[4:5]
	s_cbranch_vccnz .LBB0_597
	v_mov_b32_e32 v2, 0
	s_mov_b32 s42, s77
	s_mov_b32 s3, s78
	s_mov_b32 s59, s10
	s_mov_b32 s64, s9
	s_mov_b32 s75, s8
	v_mov_b32_e32 v3, v2
	v_mov_b32_e32 v4, v2
	v_mov_b32_e32 v5, v2
	v_mov_b32_e32 v6, v2
	v_mov_b32_e32 v7, v2
	v_mov_b32_e32 v8, v2
	v_mov_b32_e32 v9, v2
	v_mov_b32_e32 v18, v2
	v_mov_b32_e32 v19, v2
	v_mov_b32_e32 v20, v2
	v_mov_b32_e32 v21, v2
	v_mov_b32_e32 v22, v2
	v_mov_b32_e32 v23, v2
	v_mov_b32_e32 v24, v2
	v_mov_b32_e32 v25, v2
	v_mov_b32_e32 v34, v2
	v_mov_b32_e32 v35, v2
	v_mov_b32_e32 v36, v2
	v_mov_b32_e32 v37, v2
	v_mov_b32_e32 v38, v2
	v_mov_b32_e32 v39, v2
	v_mov_b32_e32 v40, v2
	v_mov_b32_e32 v41, v2
	v_mov_b32_e32 v50, v2
	v_mov_b32_e32 v51, v2
	v_mov_b32_e32 v52, v2
	v_mov_b32_e32 v53, v2
	v_mov_b32_e32 v54, v2
	v_mov_b32_e32 v55, v2
	v_mov_b32_e32 v56, v2
	v_mov_b32_e32 v57, v2
	v_mov_b32_e32 v10, v2
	v_mov_b32_e32 v11, v2
	v_mov_b32_e32 v12, v2
	v_mov_b32_e32 v13, v2
	v_mov_b32_e32 v14, v2
	v_mov_b32_e32 v15, v2
	v_mov_b32_e32 v16, v2
	v_mov_b32_e32 v17, v2
	v_mov_b32_e32 v26, v2
	v_mov_b32_e32 v27, v2
	v_mov_b32_e32 v28, v2
	v_mov_b32_e32 v29, v2
	v_mov_b32_e32 v30, v2
	v_mov_b32_e32 v31, v2
	v_mov_b32_e32 v32, v2
	v_mov_b32_e32 v33, v2
	v_mov_b32_e32 v42, v2
	v_mov_b32_e32 v43, v2
	v_mov_b32_e32 v44, v2
	v_mov_b32_e32 v45, v2
	v_mov_b32_e32 v46, v2
	v_mov_b32_e32 v47, v2
	v_mov_b32_e32 v48, v2
	v_mov_b32_e32 v49, v2
	v_mov_b32_e32 v58, v2
	v_mov_b32_e32 v59, v2
	v_mov_b32_e32 v60, v2
	v_mov_b32_e32 v61, v2
	v_mov_b32_e32 v62, v2
	v_mov_b32_e32 v63, v2
	v_mov_b32_e32 v64, v2
	v_mov_b32_e32 v65, v2
	v_mov_b32_e32 v66, v2
	v_mov_b32_e32 v67, v2
	v_mov_b32_e32 v68, v2
	v_mov_b32_e32 v69, v2
	v_mov_b32_e32 v70, v2
	v_mov_b32_e32 v71, v2
	v_mov_b32_e32 v72, v2
	v_mov_b32_e32 v73, v2
	v_mov_b32_e32 v82, v2
	v_mov_b32_e32 v83, v2
	v_mov_b32_e32 v84, v2
	v_mov_b32_e32 v85, v2
	v_mov_b32_e32 v86, v2
	v_mov_b32_e32 v87, v2
	v_mov_b32_e32 v88, v2
	v_mov_b32_e32 v89, v2
	v_mov_b32_e32 v98, v2
	v_mov_b32_e32 v99, v2
	v_mov_b32_e32 v100, v2
	v_mov_b32_e32 v101, v2
	v_mov_b32_e32 v102, v2
	v_mov_b32_e32 v103, v2
	v_mov_b32_e32 v104, v2
	v_mov_b32_e32 v105, v2
	v_mov_b32_e32 v114, v2
	v_mov_b32_e32 v115, v2
	v_mov_b32_e32 v116, v2
	v_mov_b32_e32 v117, v2
	v_mov_b32_e32 v118, v2
	v_mov_b32_e32 v119, v2
	v_mov_b32_e32 v120, v2
	v_mov_b32_e32 v121, v2
	v_mov_b32_e32 v74, v2
	v_mov_b32_e32 v75, v2
	v_mov_b32_e32 v76, v2
	v_mov_b32_e32 v77, v2
	v_mov_b32_e32 v78, v2
	v_mov_b32_e32 v79, v2
	v_mov_b32_e32 v80, v2
	v_mov_b32_e32 v81, v2
	v_mov_b32_e32 v90, v2
	v_mov_b32_e32 v91, v2
	v_mov_b32_e32 v92, v2
	v_mov_b32_e32 v93, v2
	v_mov_b32_e32 v94, v2
	v_mov_b32_e32 v95, v2
	v_mov_b32_e32 v96, v2
	v_mov_b32_e32 v97, v2
	v_mov_b32_e32 v106, v2
	v_mov_b32_e32 v107, v2
	v_mov_b32_e32 v108, v2
	v_mov_b32_e32 v109, v2
	v_mov_b32_e32 v110, v2
	v_mov_b32_e32 v111, v2
	v_mov_b32_e32 v112, v2
	v_mov_b32_e32 v113, v2
	v_mov_b32_e32 v122, v2
	v_mov_b32_e32 v123, v2
	v_mov_b32_e32 v124, v2
	v_mov_b32_e32 v125, v2
	v_mov_b32_e32 v126, v2
	v_mov_b32_e32 v127, v2
	v_mov_b32_e32 v128, v2
	v_mov_b32_e32 v129, v2
	s_branch .LBB0_597

.Lprio_3:
.LBB0_822:
	ds_read_b128 v[66:69], v242
	ds_read_b128 v[70:73], v242 offset:1024
	ds_read_b128 v[74:77], v242 offset:2048
	ds_read_b128 v[78:81], v242 offset:3072
	ds_read_b128 v[82:85], v243
	ds_read_b128 v[86:89], v243 offset:1024
	ds_read_b128 v[90:93], v243 offset:2048
	ds_read_b128 v[94:97], v243 offset:3072
	s_add_i32 s43, s68, 0xfff80080
	s_cmp_eq_u32 s69, 28
	s_cselect_b32 s91, s11, s67
	s_cselect_b32 s92, s10, s43
	s_add_i32 s43, s68, 0xfff80000
	s_mov_b32 m0, s79
	ds_read_b128 v[98:101], v244
	ds_read_b128 v[102:105], v244 offset:1024
	buffer_load_dwordx4 v1, s[48:51], s43 offen lds
	s_mov_b32 m0, s80
	ds_read_b128 v[106:109], v244 offset:2048
	ds_read_b128 v[110:113], v244 offset:3072
	buffer_load_dwordx4 v236, s[48:51], s43 offen lds
	s_mov_b32 m0, s81
	ds_read_b128 v[114:117], v244 offset:4096
	ds_read_b128 v[118:121], v244 offset:5120
	buffer_load_dwordx4 v1, s[48:51], s68 offen lds
	s_mov_b32 m0, s82
	ds_read_b128 v[122:125], v244 offset:6144
	ds_read_b128 v[126:129], v244 offset:7168
	buffer_load_dwordx4 v236, s[48:51], s68 offen lds
	s_waitcnt vmcnt(8)
	s_waitcnt lgkmcnt(0)
	s_barrier
	s_waitcnt lgkmcnt(0)
	v_mfma_f32_16x16x32_bf16 v[190:193], v[66:69], v[98:101], v[190:193]
	v_mfma_f32_16x16x32_bf16 v[190:193], v[70:73], v[102:105], v[190:193]
	v_mfma_f32_16x16x32_bf16 v[174:177], v[70:73], v[110:113], v[174:177]
	v_mfma_f32_16x16x32_bf16 v[174:177], v[66:69], v[106:109], v[174:177]
	v_mfma_f32_16x16x32_bf16 v[170:173], v[66:69], v[114:117], v[170:173]
	v_mfma_f32_16x16x32_bf16 v[170:173], v[70:73], v[118:121], v[170:173]
	v_mfma_f32_16x16x32_bf16 v[158:161], v[70:73], v[126:129], v[158:161]
	v_mfma_f32_16x16x32_bf16 v[158:161], v[66:69], v[122:125], v[158:161]
	v_mfma_f32_16x16x32_bf16 v[154:157], v[78:81], v[126:129], v[154:157]
	v_mfma_f32_16x16x32_bf16 v[154:157], v[74:77], v[122:125], v[154:157]
	v_mfma_f32_16x16x32_bf16 v[162:165], v[74:77], v[114:117], v[162:165]
	v_mfma_f32_16x16x32_bf16 v[162:165], v[78:81], v[118:121], v[162:165]
	v_mfma_f32_16x16x32_bf16 v[166:169], v[78:81], v[110:113], v[166:169]
	v_mfma_f32_16x16x32_bf16 v[166:169], v[74:77], v[106:109], v[166:169]
	v_mfma_f32_16x16x32_bf16 v[186:189], v[74:77], v[98:101], v[186:189]
	v_mfma_f32_16x16x32_bf16 v[186:189], v[78:81], v[102:105], v[186:189]
	v_mfma_f32_16x16x32_bf16 v[182:185], v[82:85], v[98:101], v[182:185]
	v_mfma_f32_16x16x32_bf16 v[182:185], v[86:89], v[102:105], v[182:185]
	v_mfma_f32_16x16x32_bf16 v[98:101], v[90:93], v[98:101], v[178:181]
	v_mfma_f32_16x16x32_bf16 v[98:101], v[94:97], v[102:105], v[98:101]
	v_mfma_f32_16x16x32_bf16 v[102:105], v[82:85], v[106:109], v[150:153]
	v_mfma_f32_16x16x32_bf16 v[102:105], v[86:89], v[110:113], v[102:105]
	v_mfma_f32_16x16x32_bf16 v[106:109], v[90:93], v[106:109], v[142:145]
	v_mfma_f32_16x16x32_bf16 v[106:109], v[94:97], v[110:113], v[106:109]
	v_mfma_f32_16x16x32_bf16 v[110:113], v[82:85], v[114:117], v[146:149]
	v_mfma_f32_16x16x32_bf16 v[110:113], v[86:89], v[118:121], v[110:113]
	v_mfma_f32_16x16x32_bf16 v[114:117], v[90:93], v[114:117], v[138:141]
	v_mfma_f32_16x16x32_bf16 v[114:117], v[94:97], v[118:121], v[114:117]
	v_mfma_f32_16x16x32_bf16 v[118:121], v[82:85], v[122:125], v[134:137]
	v_mfma_f32_16x16x32_bf16 v[118:121], v[86:89], v[126:129], v[118:121]
	v_mfma_f32_16x16x32_bf16 v[122:125], v[90:93], v[122:125], v[130:133]
	v_mfma_f32_16x16x32_bf16 v[122:125], v[94:97], v[126:129], v[122:125]
	s_barrier
	s_mov_b32 m0, s29
	s_mov_b32 s43, s51
	ds_read_b128 v[126:129], v244 offset:16384
	ds_read_b128 v[130:133], v244 offset:17408
	buffer_load_dwordx4 v227, s[40:43], s91 offen lds
	s_mov_b32 m0, s35
	ds_read_b128 v[134:137], v244 offset:18432
	ds_read_b128 v[138:141], v244 offset:19456
	buffer_load_dwordx4 v237, s[40:43], s91 offen lds
	s_add_i32 s93, s91, 0x1600000
	s_mov_b32 m0, s63
	ds_read_b128 v[142:145], v244 offset:20480
	ds_read_b128 v[146:149], v244 offset:21504
	buffer_load_dwordx4 v227, s[40:43], s93 offen lds
	s_mov_b32 m0, s65
	ds_read_b128 v[150:153], v244 offset:22528
	ds_read_b128 v[178:181], v244 offset:23552
	buffer_load_dwordx4 v237, s[40:43], s93 offen lds
	s_waitcnt vmcnt(6)
	s_waitcnt lgkmcnt(0)
	s_barrier
	s_waitcnt lgkmcnt(0)
	v_mfma_f32_16x16x32_bf16 v[62:65], v[66:69], v[126:129], v[62:65]
	v_mfma_f32_16x16x32_bf16 v[62:65], v[70:73], v[130:133], v[62:65]
	v_mfma_f32_16x16x32_bf16 v[46:49], v[70:73], v[138:141], v[46:49]
	v_mfma_f32_16x16x32_bf16 v[46:49], v[66:69], v[134:137], v[46:49]
	v_mfma_f32_16x16x32_bf16 v[42:45], v[66:69], v[142:145], v[42:45]
	v_mfma_f32_16x16x32_bf16 v[42:45], v[70:73], v[146:149], v[42:45]
	v_mfma_f32_16x16x32_bf16 v[30:33], v[70:73], v[178:181], v[30:33]
	v_mfma_f32_16x16x32_bf16 v[30:33], v[66:69], v[150:153], v[30:33]
	v_mfma_f32_16x16x32_bf16 v[26:29], v[78:81], v[178:181], v[26:29]
	v_mfma_f32_16x16x32_bf16 v[26:29], v[74:77], v[150:153], v[26:29]
	v_mfma_f32_16x16x32_bf16 v[34:37], v[74:77], v[142:145], v[34:37]
	v_mfma_f32_16x16x32_bf16 v[34:37], v[78:81], v[146:149], v[34:37]
	v_mfma_f32_16x16x32_bf16 v[38:41], v[78:81], v[138:141], v[38:41]
	v_mfma_f32_16x16x32_bf16 v[38:41], v[74:77], v[134:137], v[38:41]
	v_mfma_f32_16x16x32_bf16 v[58:61], v[74:77], v[126:129], v[58:61]
	v_mfma_f32_16x16x32_bf16 v[58:61], v[78:81], v[130:133], v[58:61]
	v_mfma_f32_16x16x32_bf16 v[54:57], v[82:85], v[126:129], v[54:57]
	v_mfma_f32_16x16x32_bf16 v[54:57], v[86:89], v[130:133], v[54:57]
	v_mfma_f32_16x16x32_bf16 v[22:25], v[86:89], v[138:141], v[22:25]
	v_mfma_f32_16x16x32_bf16 v[22:25], v[82:85], v[134:137], v[22:25]
	v_mfma_f32_16x16x32_bf16 v[18:21], v[82:85], v[142:145], v[18:21]
	v_mfma_f32_16x16x32_bf16 v[18:21], v[86:89], v[146:149], v[18:21]
	v_mfma_f32_16x16x32_bf16 v[6:9], v[86:89], v[178:181], v[6:9]
	v_mfma_f32_16x16x32_bf16 v[6:9], v[82:85], v[150:153], v[6:9]
	v_mfma_f32_16x16x32_bf16 v[2:5], v[94:97], v[178:181], v[2:5]
	v_mfma_f32_16x16x32_bf16 v[2:5], v[90:93], v[150:153], v[2:5]
	v_mfma_f32_16x16x32_bf16 v[10:13], v[90:93], v[142:145], v[10:13]
	v_mfma_f32_16x16x32_bf16 v[10:13], v[94:97], v[146:149], v[10:13]
	v_mfma_f32_16x16x32_bf16 v[14:17], v[94:97], v[138:141], v[14:17]
	v_mfma_f32_16x16x32_bf16 v[14:17], v[90:93], v[134:137], v[14:17]
	v_mfma_f32_16x16x32_bf16 v[50:53], v[90:93], v[126:129], v[50:53]
	v_mfma_f32_16x16x32_bf16 v[50:53], v[94:97], v[130:133], v[50:53]
	s_barrier
	ds_read_b128 v[66:69], v245
	ds_read_b128 v[70:73], v245 offset:1024
	ds_read_b128 v[74:77], v245 offset:2048
	ds_read_b128 v[78:81], v245 offset:3072
	ds_read_b128 v[82:85], v246
	ds_read_b128 v[86:89], v246 offset:1024
	ds_read_b128 v[90:93], v246 offset:2048
	ds_read_b128 v[94:97], v246 offset:3072
	s_mov_b32 m0, s3
	ds_read_b128 v[126:129], v244 offset:32768
	ds_read_b128 v[130:133], v244 offset:33792
	buffer_load_dwordx4 v1, s[48:51], s92 offen lds
	s_mov_b32 m0, s70
	ds_read_b128 v[134:137], v244 offset:34816
	ds_read_b128 v[138:141], v244 offset:35840
	buffer_load_dwordx4 v236, s[48:51], s92 offen lds
	s_add_i32 s92, s92, 0x80000
	s_mov_b32 m0, s71
	ds_read_b128 v[194:197], v244 offset:36864
	ds_read_b128 v[198:201], v244 offset:37888
	buffer_load_dwordx4 v1, s[48:51], s92 offen lds
	s_mov_b32 m0, s72
	ds_read_b128 v[202:205], v244 offset:38912
	ds_read_b128 v[206:209], v244 offset:39936
	buffer_load_dwordx4 v236, s[48:51], s92 offen lds
	s_waitcnt vmcnt(8)
	s_waitcnt lgkmcnt(0)
	s_barrier
	s_waitcnt lgkmcnt(0)
	v_mfma_f32_16x16x32_bf16 v[142:145], v[66:69], v[126:129], v[190:193]
	v_mfma_f32_16x16x32_bf16 v[190:193], v[70:73], v[130:133], v[142:145]
	v_mfma_f32_16x16x32_bf16 v[142:145], v[74:77], v[126:129], v[186:189]
	v_mfma_f32_16x16x32_bf16 v[186:189], v[78:81], v[130:133], v[142:145]
	v_mfma_f32_16x16x32_bf16 v[142:145], v[66:69], v[134:137], v[174:177]
	v_mfma_f32_16x16x32_bf16 v[174:177], v[70:73], v[138:141], v[142:145]
	v_mfma_f32_16x16x32_bf16 v[142:145], v[74:77], v[134:137], v[166:169]
	v_mfma_f32_16x16x32_bf16 v[166:169], v[78:81], v[138:141], v[142:145]
	v_mfma_f32_16x16x32_bf16 v[142:145], v[66:69], v[194:197], v[170:173]
	v_mfma_f32_16x16x32_bf16 v[170:173], v[70:73], v[198:201], v[142:145]
	v_mfma_f32_16x16x32_bf16 v[142:145], v[74:77], v[194:197], v[162:165]
	v_mfma_f32_16x16x32_bf16 v[162:165], v[78:81], v[198:201], v[142:145]
	v_mfma_f32_16x16x32_bf16 v[142:145], v[66:69], v[202:205], v[158:161]
	v_mfma_f32_16x16x32_bf16 v[158:161], v[70:73], v[206:209], v[142:145]
	v_mfma_f32_16x16x32_bf16 v[142:145], v[74:77], v[202:205], v[154:157]
	v_mfma_f32_16x16x32_bf16 v[154:157], v[78:81], v[206:209], v[142:145]
	v_mfma_f32_16x16x32_bf16 v[98:101], v[90:93], v[126:129], v[98:101]
	v_mfma_f32_16x16x32_bf16 v[178:181], v[94:97], v[130:133], v[98:101]
	v_mfma_f32_16x16x32_bf16 v[142:145], v[82:85], v[126:129], v[182:185]
	v_mfma_f32_16x16x32_bf16 v[182:185], v[86:89], v[130:133], v[142:145]
	v_mfma_f32_16x16x32_bf16 v[98:101], v[82:85], v[134:137], v[102:105]
	v_mfma_f32_16x16x32_bf16 v[150:153], v[86:89], v[138:141], v[98:101]
	v_mfma_f32_16x16x32_bf16 v[98:101], v[90:93], v[134:137], v[106:109]
	v_mfma_f32_16x16x32_bf16 v[142:145], v[94:97], v[138:141], v[98:101]
	v_mfma_f32_16x16x32_bf16 v[98:101], v[82:85], v[194:197], v[110:113]
	v_mfma_f32_16x16x32_bf16 v[146:149], v[86:89], v[198:201], v[98:101]
	v_mfma_f32_16x16x32_bf16 v[98:101], v[90:93], v[194:197], v[114:117]
	v_mfma_f32_16x16x32_bf16 v[138:141], v[94:97], v[198:201], v[98:101]
	v_mfma_f32_16x16x32_bf16 v[98:101], v[82:85], v[202:205], v[118:121]
	v_mfma_f32_16x16x32_bf16 v[134:137], v[86:89], v[206:209], v[98:101]
	v_mfma_f32_16x16x32_bf16 v[98:101], v[90:93], v[202:205], v[122:125]
	v_mfma_f32_16x16x32_bf16 v[130:133], v[94:97], v[206:209], v[98:101]
	s_barrier
	s_mov_b32 m0, s74
	s_or_b32 s92, s91, 0x80
	s_nop 2
	ds_read_b128 v[98:101], v244 offset:49152
	ds_read_b128 v[102:105], v244 offset:50176
	buffer_load_dwordx4 v227, s[40:43], s92 offen lds
	s_mov_b32 m0, s75
	ds_read_b128 v[106:109], v244 offset:51200
	ds_read_b128 v[110:113], v244 offset:52224
	buffer_load_dwordx4 v237, s[40:43], s92 offen lds
	s_add_i32 s91, s91, 0x1600080
	s_mov_b32 m0, s77
	ds_read_b128 v[114:117], v244 offset:53248
	ds_read_b128 v[118:121], v244 offset:54272
	buffer_load_dwordx4 v227, s[40:43], s91 offen lds
	s_mov_b32 m0, s78
	ds_read_b128 v[122:125], v244 offset:55296
	ds_read_b128 v[126:129], v244 offset:56320
	buffer_load_dwordx4 v237, s[40:43], s91 offen lds
	s_add_i32 s69, s69, 2
	s_addk_i32 s67, 0x100
	s_addk_i32 s68, 0x100
	s_cmp_gt_u32 s69, 29
	s_waitcnt vmcnt(6)
	s_waitcnt lgkmcnt(0)
	s_barrier
	s_waitcnt lgkmcnt(0)
	v_mfma_f32_16x16x32_bf16 v[62:65], v[66:69], v[98:101], v[62:65]
	v_mfma_f32_16x16x32_bf16 v[62:65], v[70:73], v[102:105], v[62:65]
	v_mfma_f32_16x16x32_bf16 v[46:49], v[70:73], v[110:113], v[46:49]
	v_mfma_f32_16x16x32_bf16 v[46:49], v[66:69], v[106:109], v[46:49]
	v_mfma_f32_16x16x32_bf16 v[42:45], v[66:69], v[114:117], v[42:45]
	v_mfma_f32_16x16x32_bf16 v[42:45], v[70:73], v[118:121], v[42:45]
	v_mfma_f32_16x16x32_bf16 v[30:33], v[70:73], v[126:129], v[30:33]
	v_mfma_f32_16x16x32_bf16 v[30:33], v[66:69], v[122:125], v[30:33]
	v_mfma_f32_16x16x32_bf16 v[26:29], v[78:81], v[126:129], v[26:29]
	v_mfma_f32_16x16x32_bf16 v[26:29], v[74:77], v[122:125], v[26:29]
	v_mfma_f32_16x16x32_bf16 v[34:37], v[74:77], v[114:117], v[34:37]
	v_mfma_f32_16x16x32_bf16 v[34:37], v[78:81], v[118:121], v[34:37]
	v_mfma_f32_16x16x32_bf16 v[38:41], v[78:81], v[110:113], v[38:41]
	v_mfma_f32_16x16x32_bf16 v[38:41], v[74:77], v[106:109], v[38:41]
	v_mfma_f32_16x16x32_bf16 v[58:61], v[74:77], v[98:101], v[58:61]
	v_mfma_f32_16x16x32_bf16 v[58:61], v[78:81], v[102:105], v[58:61]
	v_mfma_f32_16x16x32_bf16 v[54:57], v[82:85], v[98:101], v[54:57]
	v_mfma_f32_16x16x32_bf16 v[54:57], v[86:89], v[102:105], v[54:57]
	v_mfma_f32_16x16x32_bf16 v[22:25], v[86:89], v[110:113], v[22:25]
	v_mfma_f32_16x16x32_bf16 v[22:25], v[82:85], v[106:109], v[22:25]
	v_mfma_f32_16x16x32_bf16 v[18:21], v[82:85], v[114:117], v[18:21]
	v_mfma_f32_16x16x32_bf16 v[18:21], v[86:89], v[118:121], v[18:21]
	v_mfma_f32_16x16x32_bf16 v[6:9], v[86:89], v[126:129], v[6:9]
	v_mfma_f32_16x16x32_bf16 v[6:9], v[82:85], v[122:125], v[6:9]
	v_mfma_f32_16x16x32_bf16 v[2:5], v[94:97], v[126:129], v[2:5]
	v_mfma_f32_16x16x32_bf16 v[2:5], v[90:93], v[122:125], v[2:5]
	v_mfma_f32_16x16x32_bf16 v[10:13], v[90:93], v[114:117], v[10:13]
	v_mfma_f32_16x16x32_bf16 v[10:13], v[94:97], v[118:121], v[10:13]
	v_mfma_f32_16x16x32_bf16 v[14:17], v[94:97], v[110:113], v[14:17]
	v_mfma_f32_16x16x32_bf16 v[14:17], v[90:93], v[106:109], v[14:17]
	v_mfma_f32_16x16x32_bf16 v[50:53], v[90:93], v[98:101], v[50:53]
	v_mfma_f32_16x16x32_bf16 v[50:53], v[94:97], v[102:105], v[50:53]
	s_barrier
	s_cbranch_scc0 .LBB0_822
	s_setprio 0
	s_and_b64 vcc, exec, s[38:39]
	s_cbranch_vccz .LBB0_825
	s_barrier
